# v47 + diff loops: bias-range scalar test hoisted out of the MFMA run (12 MFMAs per step now back to back)
# baseline (speedup 1.0000x reference)
; #define LAS __attribute__((address_space(3)))
; DI void expsum(f32x16& p, float& l_reg, bf16x8& pa0, bf16x8& pa1) {
; #pragma unroll
;     for (int r = 0; r < 16; ++r) p[r] = __builtin_amdgcn_exp2f(p[r]);
;     float ps = 0.f;
; #pragma unroll
;     for (int r = 0; r < 16; ++r) ps += p[r];
;     l_reg += ps; asm volatile("" : "+v"(l_reg));
;     ...
;     ATT_PK4(p, 0, pa0); ATT_PK4(p, 8, pa1);
;     ...
; }
; DI int v_rd_base(int lane) { return ((lane & 3) << 3) | (((lane >> 2) & 3) << 6) | (((lane >> 4) & 1) << 5) | (((lane >> 5) & 1) << 8); }
; template <int OFF> DI s16x4 tr_read(int vb) { s16x4 r; asm volatile("ds_read_b64_tr_b16 %0, %1 offset:%2" : "=&v"(r) : "v"(vb), "i"(OFF) : "memory"); return r; }
; template <int H> DI void v_reads(s16x4* vf, int vb) {
;     vf[0] = tr_read<v_rd_off(0, 2 * H, 0)>(vb); vf[1] = tr_read<v_rd_off(0, 2 * H, 1)>(vb); vf[2] = tr_read<v_rd_off(0, 2 * H + 1, 0)>(vb); vf[3] = tr_read<v_rd_off(0, 2 * H + 1, 1)>(vb);
;     vf[4] = tr_read<v_rd_off(1, 2 * H, 0)>(vb); vf[5] = tr_read<v_rd_off(1, 2 * H, 1)>(vb); vf[6] = tr_read<v_rd_off(1, 2 * H + 1, 0)>(vb); vf[7] = tr_read<v_rd_off(1, 2 * H + 1, 1)>(vb);
;     vf[8] = tr_read<v_rd_off(2, 2 * H, 0)>(vb); vf[9] = tr_read<v_rd_off(2, 2 * H, 1)>(vb); vf[10] = tr_read<v_rd_off(2, 2 * H + 1, 0)>(vb); vf[11] = tr_read<v_rd_off(2, 2 * H + 1, 1)>(vb);
;     vf[12] = tr_read<v_rd_off(3, 2 * H, 0)>(vb); vf[13] = tr_read<v_rd_off(3, 2 * H, 1)>(vb); vf[14] = tr_read<v_rd_off(3, 2 * H + 1, 0)>(vb); vf[15] = tr_read<v_rd_off(3, 2 * H + 1, 1)>(vb);
; }
; DI void pv_mma(f32x16* o, const s16x4* vf, bf16x8 pa0, bf16x8 pa1) {
;     ...
; #pragma unroll
;     for (int d0 = 0; d0 < 4; ++d0) {
;         o[d0] = __builtin_amdgcn_mfma_f32_32x32x16_bf16(pa0, ATT_PK(vf[4 * d0], vf[4 * d0 + 1]), o[d0], 0, 0, 0);
;         o[d0] = __builtin_amdgcn_mfma_f32_32x32x16_bf16(pa1, ATT_PK(vf[4 * d0 + 2], vf[4 * d0 + 3]), o[d0], 0, 0, 0); }
;     ...
; }
; template <int DQK, int D0A, int D0B> DI void k_reads(bf16x8* kf, const LAS unsigned char* Ks, int half, int r32, int hi) {
; #pragma unroll
;     for (int d0 = D0A; d0 < D0B; ++d0) kf[d0 - D0A] = *(const LAS bf16x8*)(Ks + half * (32 * DQK * 2) + kswz<DQK>(r32, (d0 * 16 + hi * 8) * 2));
; }
; template <int D0A, int D0B> DI void qk_mma(f32x16& p, const bf16x8* kf, const bf16x8* qr) {
; #pragma unroll
;     for (int d0 = D0A; d0 < D0B; ++d0) {
.LBB0_1922:
	s_add_i32 s3, s0, -1
	s_add_i32 s2, s22, 0xffffa000
	s_and_b32 s2, s2, 0x6000
	v_add_u32_e32 v121, s2, v114
	v_add_u32_e32 v122, v121, v115
	v_add_u32_e32 v126, v121, v116
	ds_read_b128 v[122:125], v122 offset:4096
	ds_read_b128 v[132:135], v126 offset:4096
	v_add_u32_e32 v126, v121, v117
	v_add_u32_e32 v121, v121, v118
	s_lshl_b32 s2, s1, 14
	ds_read_b128 v[136:139], v126 offset:4096
	ds_read_b128 v[140:143], v121 offset:4096
	v_add_u32_e32 v121, s2, v106
	ds_read_b64_tr_b16 v[144:145], v121 offset:0
	ds_read_b64_tr_b16 v[146:147], v121 offset:0x800
	ds_read_b64_tr_b16 v[148:149], v121 offset:0x1000
	ds_read_b64_tr_b16 v[150:151], v121 offset:0x1800
	ds_read_b64_tr_b16 v[152:153], v121 offset:0x200
	ds_read_b64_tr_b16 v[154:155], v121 offset:0xa00
	ds_read_b64_tr_b16 v[156:157], v121 offset:0x1200
	ds_read_b64_tr_b16 v[158:159], v121 offset:0x1a00
	ds_read_b64_tr_b16 v[162:163], v121 offset:0x400
	ds_read_b64_tr_b16 v[164:165], v121 offset:0xc00
	ds_read_b64_tr_b16 v[166:167], v121 offset:0x1400
	ds_read_b64_tr_b16 v[168:169], v121 offset:0x1c00
	ds_read_b64_tr_b16 v[170:171], v121 offset:0x600
	ds_read_b64_tr_b16 v[172:173], v121 offset:0xe00
	ds_read_b64_tr_b16 v[174:175], v121 offset:0x1600
	ds_read_b64_tr_b16 v[176:177], v121 offset:0x1e00
	s_cmp_lt_i32 s3, s55
	s_cselect_b64 vcc, -1, 0
	s_cmp_ge_i32 s3, s97
	s_cselect_b64 s[74:75], -1, 0
	s_or_b64 s[74:75], vcc, s[74:75]
	s_and_b64 vcc, exec, s[74:75]
	s_setprio 2
	v_exp_f32_e32 v64, v64
	v_exp_f32_e32 v65, v65
	v_exp_f32_e32 v66, v66
	v_exp_f32_e32 v67, v67
	v_exp_f32_e32 v68, v68
	v_add_f32_e32 v126, 0, v64
	v_exp_f32_e32 v69, v69
	v_add_f32_e32 v126, v65, v126
	v_exp_f32_e32 v70, v70
	v_add_f32_e32 v126, v66, v126
	v_exp_f32_e32 v71, v71
	v_add_f32_e32 v126, v67, v126
	v_exp_f32_e32 v72, v72
	v_add_f32_e32 v126, v68, v126
	v_exp_f32_e32 v73, v73
	v_add_f32_e32 v126, v69, v126
	v_exp_f32_e32 v74, v74
	v_add_f32_e32 v126, v70, v126
	v_exp_f32_e32 v75, v75
	v_add_f32_e32 v126, v71, v126
	v_exp_f32_e32 v76, v76
	v_add_f32_e32 v126, v72, v126
	v_exp_f32_e32 v77, v77
	v_add_f32_e32 v126, v73, v126
	v_exp_f32_e32 v78, v78
	v_add_f32_e32 v126, v74, v126
	v_exp_f32_e32 v79, v79
	v_add_f32_e32 v126, v75, v126
	v_add_f32_e32 v126, v76, v126
	v_add_f32_e32 v126, v77, v126
	v_add_f32_e32 v126, v78, v126
	v_add_f32_e32 v126, v79, v126
	v_add_f32_e32 v120, v126, v120
	v_cvt_pk_bf16_f32 v64, v64, v65
	v_cvt_pk_bf16_f32 v65, v66, v67
	v_cvt_pk_bf16_f32 v66, v68, v69
	v_cvt_pk_bf16_f32 v67, v70, v71
	v_cvt_pk_bf16_f32 v68, v72, v73
	v_cvt_pk_bf16_f32 v69, v74, v75
	v_cvt_pk_bf16_f32 v70, v76, v77
	v_cvt_pk_bf16_f32 v71, v78, v79
	s_nop 0
	v_permlane32_swap_b32_e32 v64, v66
	v_permlane32_swap_b32_e32 v65, v67
	v_permlane32_swap_b32_e32 v68, v70
	v_permlane32_swap_b32_e32 v69, v71
	s_waitcnt lgkmcnt(0)
	s_setprio 1
	v_mfma_f32_32x32x16_bf16 v[0:15], v[64:67], v[144:147], v[0:15]
	v_mfma_f32_32x32x16_bf16 v[48:63], v[64:67], v[152:155], v[48:63]
	v_mfma_f32_32x32x16_bf16 v[32:47], v[64:67], v[162:165], v[32:47]
	v_mfma_f32_32x32x16_bf16 v[16:31], v[64:67], v[170:173], v[16:31]
	v_mfma_f32_32x32x16_bf16 v[0:15], v[68:71], v[148:151], v[0:15]
	v_mfma_f32_32x32x16_bf16 v[48:63], v[68:71], v[156:159], v[48:63]
	v_mfma_f32_32x32x16_bf16 v[32:47], v[68:71], v[166:169], v[32:47]
	v_mfma_f32_32x32x16_bf16 v[16:31], v[68:71], v[174:177], v[16:31]
	v_mfma_f32_32x32x16_bf16 v[64:79], v[122:125], v[92:95], 0
	v_mfma_f32_32x32x16_bf16 v[64:79], v[132:135], v[88:91], v[64:79]
	v_mfma_f32_32x32x16_bf16 v[64:79], v[136:139], v[84:87], v[64:79]
	v_mfma_f32_32x32x16_bf16 v[64:79], v[140:143], v[80:83], v[64:79]
	s_setprio 0
	v_add_u32_e32 v122, s7, v119
	s_cbranch_vccnz .LBB0_1924
	v_add_u32_e32 v138, 0x28908, v122
	v_add_u32_e32 v140, 0x28920, v122
	v_add_u32_e32 v142, 0x28928, v122
	v_add_u32_e32 v124, 0x28940, v122
	v_add_u32_e32 v126, 0x28948, v122
	v_add_u32_e32 v132, 0x28960, v122
	v_add_u32_e32 v134, 0x28968, v122
	v_add_u32_e32 v123, 0x28900, v122
	ds_read2_b32 v[124:125], v124 offset1:1
	ds_read2_b32 v[126:127], v126 offset1:1
	ds_read2_b32 v[132:133], v132 offset1:1
	ds_read2_b32 v[134:135], v134 offset1:1
	ds_read2_b32 v[136:137], v123 offset1:1
	ds_read2_b32 v[138:139], v138 offset1:1
	ds_read2_b32 v[140:141], v140 offset1:1
	ds_read2_b32 v[142:143], v142 offset1:1
	s_waitcnt lgkmcnt(0)
	v_pk_add_f32 v[78:79], v[78:79], v[134:135]
	v_pk_add_f32 v[76:77], v[76:77], v[132:133]
	v_pk_add_f32 v[74:75], v[74:75], v[126:127]
	v_pk_add_f32 v[72:73], v[72:73], v[124:125]
	v_pk_add_f32 v[70:71], v[70:71], v[142:143]
	v_pk_add_f32 v[68:69], v[68:69], v[140:141]
	v_pk_add_f32 v[66:67], v[66:67], v[138:139]
	v_pk_add_f32 v[64:65], v[64:65], v[136:137]
; #define LAS __attribute__((address_space(3)))
; DI void expsum(f32x16& p, float& l_reg, bf16x8& pa0, bf16x8& pa1) {
; #pragma unroll
;     for (int r = 0; r < 16; ++r) p[r] = __builtin_amdgcn_exp2f(p[r]);
;     float ps = 0.f;
; #pragma unroll
;     for (int r = 0; r < 16; ++r) ps += p[r];
;     l_reg += ps; asm volatile("" : "+v"(l_reg));
;     ...
;     ATT_PK4(p, 0, pa0); ATT_PK4(p, 8, pa1);
;     ...
; }
; DI int v_rd_base(int lane) { return ((lane & 3) << 3) | (((lane >> 2) & 3) << 6) | (((lane >> 4) & 1) << 5) | (((lane >> 5) & 1) << 8); }
; template <int OFF> DI s16x4 tr_read(int vb) { s16x4 r; asm volatile("ds_read_b64_tr_b16 %0, %1 offset:%2" : "=&v"(r) : "v"(vb), "i"(OFF) : "memory"); return r; }
; template <int H> DI void v_reads(s16x4* vf, int vb) {
;     vf[0] = tr_read<v_rd_off(0, 2 * H, 0)>(vb); vf[1] = tr_read<v_rd_off(0, 2 * H, 1)>(vb); vf[2] = tr_read<v_rd_off(0, 2 * H + 1, 0)>(vb); vf[3] = tr_read<v_rd_off(0, 2 * H + 1, 1)>(vb);
;     vf[4] = tr_read<v_rd_off(1, 2 * H, 0)>(vb); vf[5] = tr_read<v_rd_off(1, 2 * H, 1)>(vb); vf[6] = tr_read<v_rd_off(1, 2 * H + 1, 0)>(vb); vf[7] = tr_read<v_rd_off(1, 2 * H + 1, 1)>(vb);
;     vf[8] = tr_read<v_rd_off(2, 2 * H, 0)>(vb); vf[9] = tr_read<v_rd_off(2, 2 * H, 1)>(vb); vf[10] = tr_read<v_rd_off(2, 2 * H + 1, 0)>(vb); vf[11] = tr_read<v_rd_off(2, 2 * H + 1, 1)>(vb);
;     vf[12] = tr_read<v_rd_off(3, 2 * H, 0)>(vb); vf[13] = tr_read<v_rd_off(3, 2 * H, 1)>(vb); vf[14] = tr_read<v_rd_off(3, 2 * H + 1, 0)>(vb); vf[15] = tr_read<v_rd_off(3, 2 * H + 1, 1)>(vb);
; }
; DI void pv_mma(f32x16* o, const s16x4* vf, bf16x8 pa0, bf16x8 pa1) {
;     ...
; #pragma unroll
;     for (int d0 = 0; d0 < 4; ++d0) {
;         o[d0] = __builtin_amdgcn_mfma_f32_32x32x16_bf16(pa0, ATT_PK(vf[4 * d0], vf[4 * d0 + 1]), o[d0], 0, 0, 0);
;         o[d0] = __builtin_amdgcn_mfma_f32_32x32x16_bf16(pa1, ATT_PK(vf[4 * d0 + 2], vf[4 * d0 + 3]), o[d0], 0, 0, 0); }
;     ...
; }
; template <int DQK, int D0A, int D0B> DI void k_reads(bf16x8* kf, const LAS unsigned char* Ks, int half, int r32, int hi) {
; #pragma unroll
;     for (int d0 = D0A; d0 < D0B; ++d0) kf[d0 - D0A] = *(const LAS bf16x8*)(Ks + half * (32 * DQK * 2) + kswz<DQK>(r32, (d0 * 16 + hi * 8) * 2));
; }
; template <int D0A, int D0B> DI void qk_mma(f32x16& p, const bf16x8* kf, const bf16x8* qr) {
; #pragma unroll
;     for (int d0 = D0A; d0 < D0B; ++d0) {
.LBB0_1924:
	s_add_i32 s3, s22, 0xffffc000
	s_and_b32 s3, s3, 0x6000
	v_add_u32_e32 v123, s3, v114
	v_add_u32_e32 v140, v123, v118
	v_add_u32_e32 v136, v123, v117
	v_add_u32_e32 v132, v123, v116
	v_add_u32_e32 v123, v123, v115
	ds_read_b128 v[124:127], v123
	ds_read_b128 v[132:135], v132
	ds_read_b128 v[136:139], v136
	ds_read_b128 v[140:143], v140
	ds_read_b64_tr_b16 v[144:145], v121 offset:0x2000
	ds_read_b64_tr_b16 v[146:147], v121 offset:0x2800
	ds_read_b64_tr_b16 v[148:149], v121 offset:0x3000
	ds_read_b64_tr_b16 v[150:151], v121 offset:0x3800
	ds_read_b64_tr_b16 v[152:153], v121 offset:0x2200
	ds_read_b64_tr_b16 v[154:155], v121 offset:0x2a00
	ds_read_b64_tr_b16 v[156:157], v121 offset:0x3200
	ds_read_b64_tr_b16 v[158:159], v121 offset:0x3a00
	ds_read_b64_tr_b16 v[162:163], v121 offset:0x2400
	ds_read_b64_tr_b16 v[164:165], v121 offset:0x2c00
	ds_read_b64_tr_b16 v[166:167], v121 offset:0x3400
	ds_read_b64_tr_b16 v[168:169], v121 offset:0x3c00
	ds_read_b64_tr_b16 v[170:171], v121 offset:0x2600
	ds_read_b64_tr_b16 v[172:173], v121 offset:0x2e00
	ds_read_b64_tr_b16 v[174:175], v121 offset:0x3600
	ds_read_b64_tr_b16 v[176:177], v121 offset:0x3e00
	s_cmp_lt_i32 s0, s55
	s_cselect_b64 s[74:75], -1, 0
	s_cmp_ge_i32 s0, s97
	s_cselect_b64 vcc, -1, 0
	s_or_b64 s[74:75], s[74:75], vcc
	s_and_b64 vcc, exec, s[74:75]
	s_setprio 2
	v_exp_f32_e32 v64, v64
	v_exp_f32_e32 v65, v65
	v_exp_f32_e32 v66, v66
	v_exp_f32_e32 v67, v67
	v_exp_f32_e32 v68, v68
	v_add_f32_e32 v121, 0, v64
	v_exp_f32_e32 v69, v69
	v_add_f32_e32 v121, v65, v121
	v_exp_f32_e32 v70, v70
	v_add_f32_e32 v121, v66, v121
	v_exp_f32_e32 v71, v71
	v_add_f32_e32 v121, v67, v121
	v_exp_f32_e32 v72, v72
	v_add_f32_e32 v121, v68, v121
	v_exp_f32_e32 v73, v73
	v_add_f32_e32 v121, v69, v121
	v_exp_f32_e32 v74, v74
	v_add_f32_e32 v121, v70, v121
	v_exp_f32_e32 v75, v75
	v_add_f32_e32 v121, v71, v121
	v_exp_f32_e32 v76, v76
	v_add_f32_e32 v121, v72, v121
	v_exp_f32_e32 v77, v77
	v_add_f32_e32 v121, v73, v121
	v_exp_f32_e32 v78, v78
	v_add_f32_e32 v121, v74, v121
	v_exp_f32_e32 v79, v79
	v_add_f32_e32 v121, v75, v121
	v_add_f32_e32 v121, v76, v121
	v_add_f32_e32 v121, v77, v121
	v_add_f32_e32 v121, v78, v121
	v_add_f32_e32 v121, v79, v121
	v_add_f32_e32 v120, v120, v121
	v_cvt_pk_bf16_f32 v64, v64, v65
	v_cvt_pk_bf16_f32 v65, v66, v67
	v_cvt_pk_bf16_f32 v66, v68, v69
	v_cvt_pk_bf16_f32 v67, v70, v71
	v_cvt_pk_bf16_f32 v68, v72, v73
	v_cvt_pk_bf16_f32 v69, v74, v75
	v_cvt_pk_bf16_f32 v70, v76, v77
	v_cvt_pk_bf16_f32 v71, v78, v79
	s_nop 0
	v_permlane32_swap_b32_e32 v64, v66
	v_permlane32_swap_b32_e32 v65, v67
	v_permlane32_swap_b32_e32 v68, v70
	v_permlane32_swap_b32_e32 v69, v71
	s_waitcnt lgkmcnt(0)
	s_setprio 1
	s_cmp_lt_u32 s33, 0x100
	s_cbranch_scc1 .Lstg_d0_mid_11
	s_waitcnt vmcnt(3)
	s_barrier
.Lstg_d0_mid_11:
	v_mfma_f32_32x32x16_bf16 v[0:15], v[64:67], v[144:147], v[0:15]
	v_mfma_f32_32x32x16_bf16 v[48:63], v[64:67], v[152:155], v[48:63]
	v_mfma_f32_32x32x16_bf16 v[32:47], v[64:67], v[162:165], v[32:47]
	v_mfma_f32_32x32x16_bf16 v[16:31], v[64:67], v[170:173], v[16:31]
	v_mfma_f32_32x32x16_bf16 v[0:15], v[68:71], v[148:151], v[0:15]
	v_mfma_f32_32x32x16_bf16 v[48:63], v[68:71], v[156:159], v[48:63]
	v_mfma_f32_32x32x16_bf16 v[32:47], v[68:71], v[166:169], v[32:47]
	v_mfma_f32_32x32x16_bf16 v[16:31], v[68:71], v[174:177], v[16:31]
	v_mfma_f32_32x32x16_bf16 v[64:79], v[124:127], v[92:95], 0
	v_mfma_f32_32x32x16_bf16 v[64:79], v[132:135], v[88:91], v[64:79]
	v_mfma_f32_32x32x16_bf16 v[64:79], v[136:139], v[84:87], v[64:79]
	v_mfma_f32_32x32x16_bf16 v[64:79], v[140:143], v[80:83], v[64:79]
	s_cbranch_vccnz .LBB0_1926
	v_add_u32_e32 v136, 0x28988, v122
	v_add_u32_e32 v138, 0x289a0, v122
	v_add_u32_e32 v140, 0x289a8, v122
	v_add_u32_e32 v123, 0x289c0, v122
	v_add_u32_e32 v124, 0x289c8, v122
	v_add_u32_e32 v126, 0x289e0, v122
	v_add_u32_e32 v132, 0x289e8, v122
	v_add_u32_e32 v121, 0x28980, v122
	ds_read2_b32 v[122:123], v123 offset1:1
	ds_read2_b32 v[124:125], v124 offset1:1
	ds_read2_b32 v[126:127], v126 offset1:1
	ds_read2_b32 v[132:133], v132 offset1:1
	ds_read2_b32 v[134:135], v121 offset1:1
	ds_read2_b32 v[136:137], v136 offset1:1
	ds_read2_b32 v[138:139], v138 offset1:1
	ds_read2_b32 v[140:141], v140 offset1:1
	s_waitcnt lgkmcnt(0)
	v_pk_add_f32 v[78:79], v[78:79], v[132:133]
	v_pk_add_f32 v[76:77], v[76:77], v[126:127]
	v_pk_add_f32 v[74:75], v[74:75], v[124:125]
	v_pk_add_f32 v[72:73], v[72:73], v[122:123]
	v_pk_add_f32 v[70:71], v[70:71], v[140:141]
	v_pk_add_f32 v[68:69], v[68:69], v[138:139]
	v_pk_add_f32 v[66:67], v[66:67], v[136:137]
	v_pk_add_f32 v[64:65], v[64:65], v[134:135]

; #define LAS __attribute__((address_space(3)))
; DI void expsum(f32x16& p, float& l_reg, bf16x8& pa0, bf16x8& pa1) {
; #pragma unroll
;     for (int r = 0; r < 16; ++r) p[r] = __builtin_amdgcn_exp2f(p[r]);
;     float ps = 0.f;
; #pragma unroll
;     for (int r = 0; r < 16; ++r) ps += p[r];
;     l_reg += ps; asm volatile("" : "+v"(l_reg));
;     ...
;     ATT_PK4(p, 0, pa0); ATT_PK4(p, 8, pa1);
;     ...
; }
; DI int v_rd_base(int lane) { return ((lane & 3) << 3) | (((lane >> 2) & 3) << 6) | (((lane >> 4) & 1) << 5) | (((lane >> 5) & 1) << 8); }
; template <int OFF> DI s16x4 tr_read(int vb) { s16x4 r; asm volatile("ds_read_b64_tr_b16 %0, %1 offset:%2" : "=&v"(r) : "v"(vb), "i"(OFF) : "memory"); return r; }
; template <int H> DI void v_reads(s16x4* vf, int vb) {
;     vf[0] = tr_read<v_rd_off(0, 2 * H, 0)>(vb); vf[1] = tr_read<v_rd_off(0, 2 * H, 1)>(vb); vf[2] = tr_read<v_rd_off(0, 2 * H + 1, 0)>(vb); vf[3] = tr_read<v_rd_off(0, 2 * H + 1, 1)>(vb);
;     vf[4] = tr_read<v_rd_off(1, 2 * H, 0)>(vb); vf[5] = tr_read<v_rd_off(1, 2 * H, 1)>(vb); vf[6] = tr_read<v_rd_off(1, 2 * H + 1, 0)>(vb); vf[7] = tr_read<v_rd_off(1, 2 * H + 1, 1)>(vb);
;     vf[8] = tr_read<v_rd_off(2, 2 * H, 0)>(vb); vf[9] = tr_read<v_rd_off(2, 2 * H, 1)>(vb); vf[10] = tr_read<v_rd_off(2, 2 * H + 1, 0)>(vb); vf[11] = tr_read<v_rd_off(2, 2 * H + 1, 1)>(vb);
;     vf[12] = tr_read<v_rd_off(3, 2 * H, 0)>(vb); vf[13] = tr_read<v_rd_off(3, 2 * H, 1)>(vb); vf[14] = tr_read<v_rd_off(3, 2 * H + 1, 0)>(vb); vf[15] = tr_read<v_rd_off(3, 2 * H + 1, 1)>(vb);
; }
; DI void pv_mma(f32x16* o, const s16x4* vf, bf16x8 pa0, bf16x8 pa1) {
;     ...
; #pragma unroll
;     for (int d0 = 0; d0 < 4; ++d0) {
;         o[d0] = __builtin_amdgcn_mfma_f32_32x32x16_bf16(pa0, ATT_PK(vf[4 * d0], vf[4 * d0 + 1]), o[d0], 0, 0, 0);
;         o[d0] = __builtin_amdgcn_mfma_f32_32x32x16_bf16(pa1, ATT_PK(vf[4 * d0 + 2], vf[4 * d0 + 3]), o[d0], 0, 0, 0); }
;     ...
; }
; template <int DQK, int D0A, int D0B> DI void k_reads(bf16x8* kf, const LAS unsigned char* Ks, int half, int r32, int hi) {
; #pragma unroll
;     for (int d0 = D0A; d0 < D0B; ++d0) kf[d0 - D0A] = *(const LAS bf16x8*)(Ks + half * (32 * DQK * 2) + kswz<DQK>(r32, (d0 * 16 + hi * 8) * 2));
; }
; template <int D0A, int D0B> DI void qk_mma(f32x16& p, const bf16x8* kf, const bf16x8* qr) {
; #pragma unroll
;     for (int d0 = D0A; d0 < D0B; ++d0) {
.LBB0_1953:
	s_add_i32 s3, s0, -1
	s_add_i32 s2, s22, 0xffffa000
	s_and_b32 s2, s2, 0x6000
	v_add_u32_e32 v121, s2, v114
	v_add_u32_e32 v122, v121, v115
	v_add_u32_e32 v126, v121, v116
	ds_read_b128 v[122:125], v122 offset:4096
	ds_read_b128 v[132:135], v126 offset:4096
	v_add_u32_e32 v126, v121, v117
	v_add_u32_e32 v121, v121, v118
	s_lshl_b32 s2, s23, 14
	ds_read_b128 v[136:139], v126 offset:4096
	ds_read_b128 v[140:143], v121 offset:4096
	v_add_u32_e32 v121, s2, v106
	ds_read_b64_tr_b16 v[144:145], v121 offset:0
	ds_read_b64_tr_b16 v[146:147], v121 offset:0x800
	ds_read_b64_tr_b16 v[148:149], v121 offset:0x1000
	ds_read_b64_tr_b16 v[150:151], v121 offset:0x1800
	ds_read_b64_tr_b16 v[152:153], v121 offset:0x200
	ds_read_b64_tr_b16 v[154:155], v121 offset:0xa00
	ds_read_b64_tr_b16 v[156:157], v121 offset:0x1200
	ds_read_b64_tr_b16 v[158:159], v121 offset:0x1a00
	ds_read_b64_tr_b16 v[162:163], v121 offset:0x400
	ds_read_b64_tr_b16 v[164:165], v121 offset:0xc00
	ds_read_b64_tr_b16 v[166:167], v121 offset:0x1400
	ds_read_b64_tr_b16 v[168:169], v121 offset:0x1c00
	ds_read_b64_tr_b16 v[170:171], v121 offset:0x600
	ds_read_b64_tr_b16 v[172:173], v121 offset:0xe00
	ds_read_b64_tr_b16 v[174:175], v121 offset:0x1600
	ds_read_b64_tr_b16 v[176:177], v121 offset:0x1e00
	s_cmp_lt_i32 s3, s47
	s_cselect_b64 s[74:75], -1, 0
	s_cmp_ge_i32 s3, s52
	s_cselect_b64 s[90:91], -1, 0
	s_or_b64 s[74:75], s[74:75], s[90:91]
	s_and_b64 vcc, exec, s[74:75]
	s_setprio 2
	v_exp_f32_e32 v64, v64
	v_exp_f32_e32 v65, v65
	v_exp_f32_e32 v66, v66
	v_exp_f32_e32 v67, v67
	v_exp_f32_e32 v68, v68
	v_add_f32_e32 v126, 0, v64
	v_exp_f32_e32 v69, v69
	v_add_f32_e32 v126, v65, v126
	v_exp_f32_e32 v70, v70
	v_add_f32_e32 v126, v66, v126
	v_exp_f32_e32 v71, v71
	v_add_f32_e32 v126, v67, v126
	v_exp_f32_e32 v72, v72
	v_add_f32_e32 v126, v68, v126
	v_exp_f32_e32 v73, v73
	v_add_f32_e32 v126, v69, v126
	v_exp_f32_e32 v74, v74
	v_add_f32_e32 v126, v70, v126
	v_exp_f32_e32 v75, v75
	v_add_f32_e32 v126, v71, v126
	v_exp_f32_e32 v76, v76
	v_add_f32_e32 v126, v72, v126
	v_exp_f32_e32 v77, v77
	v_add_f32_e32 v126, v73, v126
	v_exp_f32_e32 v78, v78
	v_add_f32_e32 v126, v74, v126
	v_exp_f32_e32 v79, v79
	v_add_f32_e32 v126, v75, v126
	v_add_f32_e32 v126, v76, v126
	v_add_f32_e32 v126, v77, v126
	v_add_f32_e32 v126, v78, v126
	v_add_f32_e32 v126, v79, v126
	v_add_f32_e32 v120, v126, v120
	v_cvt_pk_bf16_f32 v64, v64, v65
	v_cvt_pk_bf16_f32 v65, v66, v67
	v_cvt_pk_bf16_f32 v66, v68, v69
	v_cvt_pk_bf16_f32 v67, v70, v71
	v_cvt_pk_bf16_f32 v68, v72, v73
	v_cvt_pk_bf16_f32 v69, v74, v75
	v_cvt_pk_bf16_f32 v70, v76, v77
	v_cvt_pk_bf16_f32 v71, v78, v79
	s_nop 0
	v_permlane32_swap_b32_e32 v64, v66
	v_permlane32_swap_b32_e32 v65, v67
	v_permlane32_swap_b32_e32 v68, v70
	v_permlane32_swap_b32_e32 v69, v71
	s_waitcnt lgkmcnt(0)
	s_setprio 1
	v_mfma_f32_32x32x16_bf16 v[0:15], v[64:67], v[144:147], v[0:15]
	v_mfma_f32_32x32x16_bf16 v[48:63], v[64:67], v[152:155], v[48:63]
	v_mfma_f32_32x32x16_bf16 v[16:31], v[64:67], v[162:165], v[16:31]
	v_mfma_f32_32x32x16_bf16 v[32:47], v[64:67], v[170:173], v[32:47]
	v_mfma_f32_32x32x16_bf16 v[0:15], v[68:71], v[148:151], v[0:15]
	v_mfma_f32_32x32x16_bf16 v[48:63], v[68:71], v[156:159], v[48:63]
	v_mfma_f32_32x32x16_bf16 v[16:31], v[68:71], v[166:169], v[16:31]
	v_mfma_f32_32x32x16_bf16 v[32:47], v[68:71], v[174:177], v[32:47]
	v_mfma_f32_32x32x16_bf16 v[64:79], v[122:125], v[92:95], 0
	v_mfma_f32_32x32x16_bf16 v[64:79], v[132:135], v[88:91], v[64:79]
	v_mfma_f32_32x32x16_bf16 v[64:79], v[136:139], v[84:87], v[64:79]
	v_mfma_f32_32x32x16_bf16 v[64:79], v[140:143], v[80:83], v[64:79]
	s_setprio 0
	v_add_u32_e32 v122, s7, v119
	s_cbranch_vccnz .LBB0_1955
	v_add_u32_e32 v138, 0x28908, v122
	v_add_u32_e32 v140, 0x28920, v122
	v_add_u32_e32 v142, 0x28928, v122
	v_add_u32_e32 v124, 0x28940, v122
	v_add_u32_e32 v126, 0x28948, v122
	v_add_u32_e32 v132, 0x28960, v122
	v_add_u32_e32 v134, 0x28968, v122
	v_add_u32_e32 v123, 0x28900, v122
	ds_read2_b32 v[124:125], v124 offset1:1
	ds_read2_b32 v[126:127], v126 offset1:1
	ds_read2_b32 v[132:133], v132 offset1:1
	ds_read2_b32 v[134:135], v134 offset1:1
	ds_read2_b32 v[136:137], v123 offset1:1
	ds_read2_b32 v[138:139], v138 offset1:1
	ds_read2_b32 v[140:141], v140 offset1:1
	ds_read2_b32 v[142:143], v142 offset1:1
	s_waitcnt lgkmcnt(0)
	v_pk_add_f32 v[78:79], v[78:79], v[134:135]
	v_pk_add_f32 v[76:77], v[76:77], v[132:133]
	v_pk_add_f32 v[74:75], v[74:75], v[126:127]
	v_pk_add_f32 v[72:73], v[72:73], v[124:125]
	v_pk_add_f32 v[70:71], v[70:71], v[142:143]
	v_pk_add_f32 v[68:69], v[68:69], v[140:141]
	v_pk_add_f32 v[66:67], v[66:67], v[138:139]
	v_pk_add_f32 v[64:65], v[64:65], v[136:137]
; #define LAS __attribute__((address_space(3)))
; DI void expsum(f32x16& p, float& l_reg, bf16x8& pa0, bf16x8& pa1) {
; #pragma unroll
;     for (int r = 0; r < 16; ++r) p[r] = __builtin_amdgcn_exp2f(p[r]);
;     float ps = 0.f;
; #pragma unroll
;     for (int r = 0; r < 16; ++r) ps += p[r];
;     l_reg += ps; asm volatile("" : "+v"(l_reg));
;     ...
;     ATT_PK4(p, 0, pa0); ATT_PK4(p, 8, pa1);
;     ...
; }
; DI int v_rd_base(int lane) { return ((lane & 3) << 3) | (((lane >> 2) & 3) << 6) | (((lane >> 4) & 1) << 5) | (((lane >> 5) & 1) << 8); }
; template <int OFF> DI s16x4 tr_read(int vb) { s16x4 r; asm volatile("ds_read_b64_tr_b16 %0, %1 offset:%2" : "=&v"(r) : "v"(vb), "i"(OFF) : "memory"); return r; }
; template <int H> DI void v_reads(s16x4* vf, int vb) {
;     vf[0] = tr_read<v_rd_off(0, 2 * H, 0)>(vb); vf[1] = tr_read<v_rd_off(0, 2 * H, 1)>(vb); vf[2] = tr_read<v_rd_off(0, 2 * H + 1, 0)>(vb); vf[3] = tr_read<v_rd_off(0, 2 * H + 1, 1)>(vb);
;     vf[4] = tr_read<v_rd_off(1, 2 * H, 0)>(vb); vf[5] = tr_read<v_rd_off(1, 2 * H, 1)>(vb); vf[6] = tr_read<v_rd_off(1, 2 * H + 1, 0)>(vb); vf[7] = tr_read<v_rd_off(1, 2 * H + 1, 1)>(vb);
;     vf[8] = tr_read<v_rd_off(2, 2 * H, 0)>(vb); vf[9] = tr_read<v_rd_off(2, 2 * H, 1)>(vb); vf[10] = tr_read<v_rd_off(2, 2 * H + 1, 0)>(vb); vf[11] = tr_read<v_rd_off(2, 2 * H + 1, 1)>(vb);
;     vf[12] = tr_read<v_rd_off(3, 2 * H, 0)>(vb); vf[13] = tr_read<v_rd_off(3, 2 * H, 1)>(vb); vf[14] = tr_read<v_rd_off(3, 2 * H + 1, 0)>(vb); vf[15] = tr_read<v_rd_off(3, 2 * H + 1, 1)>(vb);
; }
; DI void pv_mma(f32x16* o, const s16x4* vf, bf16x8 pa0, bf16x8 pa1) {
;     ...
; #pragma unroll
;     for (int d0 = 0; d0 < 4; ++d0) {
;         o[d0] = __builtin_amdgcn_mfma_f32_32x32x16_bf16(pa0, ATT_PK(vf[4 * d0], vf[4 * d0 + 1]), o[d0], 0, 0, 0);
;         o[d0] = __builtin_amdgcn_mfma_f32_32x32x16_bf16(pa1, ATT_PK(vf[4 * d0 + 2], vf[4 * d0 + 3]), o[d0], 0, 0, 0); }
;     ...
; }
; template <int DQK, int D0A, int D0B> DI void k_reads(bf16x8* kf, const LAS unsigned char* Ks, int half, int r32, int hi) {
; #pragma unroll
;     for (int d0 = D0A; d0 < D0B; ++d0) kf[d0 - D0A] = *(const LAS bf16x8*)(Ks + half * (32 * DQK * 2) + kswz<DQK>(r32, (d0 * 16 + hi * 8) * 2));
; }
; template <int D0A, int D0B> DI void qk_mma(f32x16& p, const bf16x8* kf, const bf16x8* qr) {
; #pragma unroll
;     for (int d0 = D0A; d0 < D0B; ++d0) {
.LBB0_1955:
	s_add_i32 s3, s22, 0xffffc000
	s_and_b32 s3, s3, 0x6000
	v_add_u32_e32 v123, s3, v114
	v_add_u32_e32 v140, v123, v118
	v_add_u32_e32 v136, v123, v117
	v_add_u32_e32 v132, v123, v116
	v_add_u32_e32 v123, v123, v115
	ds_read_b128 v[124:127], v123
	ds_read_b128 v[132:135], v132
	ds_read_b128 v[136:139], v136
	ds_read_b128 v[140:143], v140
	ds_read_b64_tr_b16 v[144:145], v121 offset:0x2000
	ds_read_b64_tr_b16 v[146:147], v121 offset:0x2800
	ds_read_b64_tr_b16 v[148:149], v121 offset:0x3000
	ds_read_b64_tr_b16 v[150:151], v121 offset:0x3800
	ds_read_b64_tr_b16 v[152:153], v121 offset:0x2200
	ds_read_b64_tr_b16 v[154:155], v121 offset:0x2a00
	ds_read_b64_tr_b16 v[156:157], v121 offset:0x3200
	ds_read_b64_tr_b16 v[158:159], v121 offset:0x3a00
	ds_read_b64_tr_b16 v[162:163], v121 offset:0x2400
	ds_read_b64_tr_b16 v[164:165], v121 offset:0x2c00
	ds_read_b64_tr_b16 v[166:167], v121 offset:0x3400
	ds_read_b64_tr_b16 v[168:169], v121 offset:0x3c00
	ds_read_b64_tr_b16 v[170:171], v121 offset:0x2600
	ds_read_b64_tr_b16 v[172:173], v121 offset:0x2e00
	ds_read_b64_tr_b16 v[174:175], v121 offset:0x3600
	ds_read_b64_tr_b16 v[176:177], v121 offset:0x3e00
	s_cmp_lt_i32 s0, s47
	s_cselect_b64 s[74:75], -1, 0
	s_cmp_ge_i32 s0, s52
	s_cselect_b64 s[90:91], -1, 0
	s_or_b64 s[74:75], s[74:75], s[90:91]
	s_and_b64 vcc, exec, s[74:75]
	s_setprio 2
	v_exp_f32_e32 v64, v64
	v_exp_f32_e32 v65, v65
	v_exp_f32_e32 v66, v66
	v_exp_f32_e32 v67, v67
	v_exp_f32_e32 v68, v68
	v_add_f32_e32 v121, 0, v64
	v_exp_f32_e32 v69, v69
	v_add_f32_e32 v121, v65, v121
	v_exp_f32_e32 v70, v70
	v_add_f32_e32 v121, v66, v121
	v_exp_f32_e32 v71, v71
	v_add_f32_e32 v121, v67, v121
	v_exp_f32_e32 v72, v72
	v_add_f32_e32 v121, v68, v121
	v_exp_f32_e32 v73, v73
	v_add_f32_e32 v121, v69, v121
	v_exp_f32_e32 v74, v74
	v_add_f32_e32 v121, v70, v121
	v_exp_f32_e32 v75, v75
	v_add_f32_e32 v121, v71, v121
	v_exp_f32_e32 v76, v76
	v_add_f32_e32 v121, v72, v121
	v_exp_f32_e32 v77, v77
	v_add_f32_e32 v121, v73, v121
	v_exp_f32_e32 v78, v78
	v_add_f32_e32 v121, v74, v121
	v_exp_f32_e32 v79, v79
	v_add_f32_e32 v121, v75, v121
	v_add_f32_e32 v121, v76, v121
	v_add_f32_e32 v121, v77, v121
	v_add_f32_e32 v121, v78, v121
	v_add_f32_e32 v121, v79, v121
	v_add_f32_e32 v120, v120, v121
	v_cvt_pk_bf16_f32 v64, v64, v65
	v_cvt_pk_bf16_f32 v65, v66, v67
	v_cvt_pk_bf16_f32 v66, v68, v69
	v_cvt_pk_bf16_f32 v67, v70, v71
	v_cvt_pk_bf16_f32 v68, v72, v73
	v_cvt_pk_bf16_f32 v69, v74, v75
	v_cvt_pk_bf16_f32 v70, v76, v77
	v_cvt_pk_bf16_f32 v71, v78, v79
	s_nop 0
	v_permlane32_swap_b32_e32 v64, v66
	v_permlane32_swap_b32_e32 v65, v67
	v_permlane32_swap_b32_e32 v68, v70
	v_permlane32_swap_b32_e32 v69, v71
	s_waitcnt lgkmcnt(0)
	s_setprio 1
	s_cmp_lt_u32 s33, 0x100
	s_cbranch_scc1 .Lstg_d1_mid_19
	s_waitcnt vmcnt(3)
	s_barrier
.Lstg_d1_mid_19:
	v_mfma_f32_32x32x16_bf16 v[0:15], v[64:67], v[144:147], v[0:15]
	v_mfma_f32_32x32x16_bf16 v[48:63], v[64:67], v[152:155], v[48:63]
	v_mfma_f32_32x32x16_bf16 v[16:31], v[64:67], v[162:165], v[16:31]
	v_mfma_f32_32x32x16_bf16 v[32:47], v[64:67], v[170:173], v[32:47]
	v_mfma_f32_32x32x16_bf16 v[0:15], v[68:71], v[148:151], v[0:15]
	v_mfma_f32_32x32x16_bf16 v[48:63], v[68:71], v[156:159], v[48:63]
	v_mfma_f32_32x32x16_bf16 v[16:31], v[68:71], v[166:169], v[16:31]
	v_mfma_f32_32x32x16_bf16 v[32:47], v[68:71], v[174:177], v[32:47]
	v_mfma_f32_32x32x16_bf16 v[64:79], v[124:127], v[92:95], 0
	v_mfma_f32_32x32x16_bf16 v[64:79], v[132:135], v[88:91], v[64:79]
	v_mfma_f32_32x32x16_bf16 v[64:79], v[136:139], v[84:87], v[64:79]
	v_mfma_f32_32x32x16_bf16 v[64:79], v[140:143], v[80:83], v[64:79]
	s_cbranch_vccnz .LBB0_1957
	v_add_u32_e32 v136, 0x28988, v122
	v_add_u32_e32 v138, 0x289a0, v122
	v_add_u32_e32 v140, 0x289a8, v122
	v_add_u32_e32 v123, 0x289c0, v122
	v_add_u32_e32 v124, 0x289c8, v122
	v_add_u32_e32 v126, 0x289e0, v122
	v_add_u32_e32 v132, 0x289e8, v122
	v_add_u32_e32 v121, 0x28980, v122
	ds_read2_b32 v[122:123], v123 offset1:1
	ds_read2_b32 v[124:125], v124 offset1:1
	ds_read2_b32 v[126:127], v126 offset1:1
	ds_read2_b32 v[132:133], v132 offset1:1
	ds_read2_b32 v[134:135], v121 offset1:1
	ds_read2_b32 v[136:137], v136 offset1:1
	ds_read2_b32 v[138:139], v138 offset1:1
	ds_read2_b32 v[140:141], v140 offset1:1
	s_waitcnt lgkmcnt(0)
	v_pk_add_f32 v[78:79], v[78:79], v[132:133]
	v_pk_add_f32 v[76:77], v[76:77], v[126:127]
	v_pk_add_f32 v[74:75], v[74:75], v[124:125]
	v_pk_add_f32 v[72:73], v[72:73], v[122:123]
	v_pk_add_f32 v[70:71], v[70:71], v[140:141]
	v_pk_add_f32 v[68:69], v[68:69], v[138:139]
	v_pk_add_f32 v[66:67], v[66:67], v[136:137]
	v_pk_add_f32 v[64:65], v[64:65], v[134:135]
